# v45 + GU GEMM K-loop back-edge rotation: loop-carried pointer bumps and next-iteration pointer selection moved from the loop bottom/top into the iteration's last MFMA block
# speedup vs baseline: 1.0006x; 1.0006x over previous
; template <class Epi, class Sched, bool ALIGN_EPI = false, bool SP2 = false>
; __device__ __forceinline__ void gemm_phase(PG8_LAS unsigned char* lds, const Gemm g, const Sched& S, const Epi& E) {
;     ...
;         const bool has_next = S.next(ui + 1, nxt);
;         const char* nA = has_next ? (const char*)g.A + (size_t)nxt.pm * tstep : cA; const char* nB = has_next ? (const char*)g.Bt + (size_t)nxt.pn * tstep : cB;
;         for (int t = 0; t < nt; t += 2) {
;             const bool last = (t == nt - 2);
;             const char* a1 = cA + (size_t)(t + 1) * kstep;
;             const char* a2 = last ? nA : cA + (size_t)(t + 2) * kstep; const char* b2 = last ? nB : cB + (size_t)(t + 2) * kstep;
;             const char* a3 = a2 + kstep; const char* b3 = b2 + kstep;
;     ...
;         for (int a = 0; a < 2; ++a)
; #pragma unroll
;             for (int b = 0; b < 2; ++b)
; #pragma unroll
;                 for (int m = 0; m < 4; ++m)
; #pragma unroll
;                     for (int n = 0; n < 2; ++n) acc[a][b][m][n] = (f32x4){0.f, 0.f, 0.f, 0.f};
.LBB0_398:
	s_ashr_i32 s41, s40, 31
	s_lshl_b64 s[14:15], s[40:41], 19
	s_add_u32 s42, s0, s14
	s_addc_u32 s43, s1, s15
	s_and_b64 s[14:15], s[38:39], exec
	s_cselect_b32 s41, s43, s11
	s_cselect_b32 s46, s42, s10
	s_ashr_i32 s9, s8, 31
	s_lshl_b64 s[14:15], s[8:9], 19
	s_add_u32 s44, s19, s14
	s_addc_u32 s45, s20, s15
	s_and_b64 s[14:15], s[38:39], exec
	s_cselect_b32 s9, s45, s13
	s_cselect_b32 s47, s44, s12
	s_add_u32 s10, s10, 0x40080
	s_addc_u32 s11, s11, 0
	s_add_u32 s48, s12, 0x100
	v_mov_b32_e32 v0, 0
	s_addc_u32 s49, s13, 0
	s_mov_b32 s50, -2
	s_add_u32 s12, s10, 0xfffc0080
	s_addc_u32 s13, s11, -1
	s_add_i32 s51, 0, 0x10000
	s_cmp_eq_u32 s50, 12
	s_cselect_b32 s15, s41, s13
	s_cselect_b32 s14, s46, s12
	s_cselect_b32 s13, s9, s49
	s_cselect_b32 s12, s47, s48
	s_add_i32 s54, 0, 0x14000
	v_mov_b32_e32 v1, v0
	v_mov_b32_e32 v2, v0
	v_mov_b32_e32 v3, v0
	v_mov_b32_e32 v4, v0
	v_mov_b32_e32 v5, v0
	v_mov_b32_e32 v6, v0
	v_mov_b32_e32 v7, v0
	v_mov_b32_e32 v16, v0
	v_mov_b32_e32 v17, v0
	v_mov_b32_e32 v18, v0
	v_mov_b32_e32 v19, v0
	v_mov_b32_e32 v20, v0
	v_mov_b32_e32 v21, v0
	v_mov_b32_e32 v22, v0
	v_mov_b32_e32 v23, v0
	v_mov_b32_e32 v32, v0
	v_mov_b32_e32 v33, v0
	v_mov_b32_e32 v34, v0
	v_mov_b32_e32 v35, v0
	v_mov_b32_e32 v36, v0
	v_mov_b32_e32 v37, v0
	v_mov_b32_e32 v38, v0
	v_mov_b32_e32 v39, v0
	v_mov_b32_e32 v48, v0
	v_mov_b32_e32 v49, v0
	v_mov_b32_e32 v50, v0
	v_mov_b32_e32 v51, v0
	v_mov_b32_e32 v52, v0
	v_mov_b32_e32 v53, v0
	v_mov_b32_e32 v54, v0
	v_mov_b32_e32 v55, v0
	v_mov_b32_e32 v8, v0
	v_mov_b32_e32 v9, v0
	v_mov_b32_e32 v10, v0
	v_mov_b32_e32 v11, v0
	v_mov_b32_e32 v12, v0
	v_mov_b32_e32 v13, v0
	v_mov_b32_e32 v14, v0
	v_mov_b32_e32 v15, v0
	v_mov_b32_e32 v24, v0
	v_mov_b32_e32 v25, v0
	v_mov_b32_e32 v26, v0
	v_mov_b32_e32 v27, v0
	v_mov_b32_e32 v28, v0
	v_mov_b32_e32 v29, v0
	v_mov_b32_e32 v30, v0
	v_mov_b32_e32 v31, v0
	v_mov_b32_e32 v40, v0
	v_mov_b32_e32 v41, v0
	v_mov_b32_e32 v42, v0
	v_mov_b32_e32 v43, v0
	v_mov_b32_e32 v44, v0
	v_mov_b32_e32 v45, v0
	v_mov_b32_e32 v46, v0
	v_mov_b32_e32 v47, v0
	v_mov_b32_e32 v56, v0
	v_mov_b32_e32 v57, v0
	v_mov_b32_e32 v58, v0
	v_mov_b32_e32 v59, v0
	v_mov_b32_e32 v60, v0
	v_mov_b32_e32 v61, v0
	v_mov_b32_e32 v62, v0
	v_mov_b32_e32 v63, v0
	v_mov_b32_e32 v64, v0
	v_mov_b32_e32 v65, v0
	v_mov_b32_e32 v66, v0
	v_mov_b32_e32 v67, v0
	v_mov_b32_e32 v68, v0
	v_mov_b32_e32 v69, v0
	v_mov_b32_e32 v70, v0
	v_mov_b32_e32 v71, v0
	v_mov_b32_e32 v80, v0
	v_mov_b32_e32 v81, v0
	v_mov_b32_e32 v82, v0
	v_mov_b32_e32 v83, v0
	v_mov_b32_e32 v84, v0
	v_mov_b32_e32 v85, v0
	v_mov_b32_e32 v86, v0
	v_mov_b32_e32 v87, v0
	v_mov_b32_e32 v96, v0
	v_mov_b32_e32 v97, v0
	v_mov_b32_e32 v98, v0
	v_mov_b32_e32 v99, v0
	v_mov_b32_e32 v100, v0
	v_mov_b32_e32 v101, v0
	v_mov_b32_e32 v102, v0
	v_mov_b32_e32 v103, v0
	v_mov_b32_e32 v112, v0
	v_mov_b32_e32 v113, v0
	v_mov_b32_e32 v114, v0
	v_mov_b32_e32 v115, v0
	v_mov_b32_e32 v116, v0
	v_mov_b32_e32 v117, v0
	v_mov_b32_e32 v118, v0
	v_mov_b32_e32 v119, v0
	v_mov_b32_e32 v72, v0
	v_mov_b32_e32 v73, v0
	v_mov_b32_e32 v74, v0
	v_mov_b32_e32 v75, v0
	v_mov_b32_e32 v76, v0
	v_mov_b32_e32 v77, v0
	v_mov_b32_e32 v78, v0
	v_mov_b32_e32 v79, v0
	v_mov_b32_e32 v88, v0
	v_mov_b32_e32 v89, v0
	v_mov_b32_e32 v90, v0
	v_mov_b32_e32 v91, v0
	v_mov_b32_e32 v92, v0
	v_mov_b32_e32 v93, v0
	v_mov_b32_e32 v94, v0
	v_mov_b32_e32 v95, v0
	v_mov_b32_e32 v104, v0
	v_mov_b32_e32 v105, v0
	v_mov_b32_e32 v106, v0
	v_mov_b32_e32 v107, v0
	v_mov_b32_e32 v108, v0
	v_mov_b32_e32 v109, v0
	v_mov_b32_e32 v110, v0
	v_mov_b32_e32 v111, v0
	v_mov_b32_e32 v120, v0
	v_mov_b32_e32 v121, v0
	v_mov_b32_e32 v122, v0
	v_mov_b32_e32 v123, v0
	v_mov_b32_e32 v124, v0
	v_mov_b32_e32 v125, v0
	v_mov_b32_e32 v126, v0
	v_mov_b32_e32 v127, v0
	.p2align 6
.LBB0_399:
	v_add_u32_e32 v146, s51, v149
	ds_read_b128 v[138:141], v146
	ds_read_b128 v[142:145], v146 offset:1024
	ds_read_b128 v[168:171], v146 offset:2048
	ds_read_b128 v[172:175], v146 offset:3072
	v_add_u32_e32 v146, s54, v149
	ds_read_b128 v[176:179], v146
	ds_read_b128 v[180:183], v146 offset:1024
	ds_read_b128 v[184:187], v146 offset:2048
	ds_read_b128 v[188:191], v146 offset:3072
	v_lshl_add_u64 v[146:147], s[10:11], 0, v[134:135]
	s_add_i32 m0, s25, 0xc000
	ds_read_b128 v[192:195], v152
	ds_read_b128 v[196:199], v152 offset:1024
	ds_read_b128 v[200:203], v152 offset:2048
	ds_read_b128 v[204:207], v152 offset:3072
	ds_read_b128 v[208:211], v152 offset:4096
	ds_read_b128 v[212:215], v152 offset:5120
	ds_read_b128 v[216:219], v152 offset:6144
	ds_read_b128 v[220:223], v152 offset:7168
	global_load_lds_dwordx4 v[146:147], off
	v_lshl_add_u64 v[146:147], s[10:11], 0, v[136:137]
	s_add_i32 m0, s25, 0xe000
	s_nop 0
	global_load_lds_dwordx4 v[146:147], off
	s_waitcnt vmcnt(8)
	s_waitcnt lgkmcnt(0)
	s_barrier
; #define PG8_STAGE(bufoff, gbase, voff) do { _Pragma("unroll") for (int _i = 0; _i < 2; ++_i) \
;         __builtin_amdgcn_global_load_lds((const unsigned*)((const char*)(gbase) + (voff)[_i]), (PG8_LAS unsigned*)(lds + (bufoff) + ldsw + _i * 8192), 16, 0, 0); } while (0)
; #define PG8_LDA(dst, b, h) do { _Pragma("unroll") for (int m = 0; m < 4; ++m) _Pragma("unroll") for (int k = 0; k < 2; ++k) dst[m][k] = *(const PG8_LAS bf16x8*)(lds + PG8_SA(b, h) + aoff + m * 2048 + k * 1024); } while (0)
; #define PG8_LDB(dst, b, h) do { _Pragma("unroll") for (int n = 0; n < 2; ++n) _Pragma("unroll") for (int k = 0; k < 2; ++k) dst[n][k] = *(const PG8_LAS bf16x8*)(lds + PG8_SB(b, h) + boff + n * 2048 + k * 1024); } while (0)
; #define PG8_MMA(ai, bj, At, Bt) do { __builtin_amdgcn_s_setprio(1); _Pragma("unroll") for (int m = 0; m < 4; ++m) _Pragma("unroll") for (int n = 0; n < 2; ++n) _Pragma("unroll") for (int k = 0; k < 2; ++k) \
;         acc[ai][bj][m][n] = __builtin_amdgcn_mfma_f32_16x16x32_bf16(Bt[n][k], At[m][k], acc[ai][bj][m][n], 0, 0, 0); __builtin_amdgcn_s_setprio(0); } while (0)
; #define PG8_WAIT_V(n) asm volatile("s_waitcnt vmcnt(" #n ")" ::: "memory")
; #define PG8_WAIT_L(n) asm volatile("s_waitcnt lgkmcnt(" #n ")" ::: "memory")
; #define PG8_BAR __builtin_amdgcn_s_barrier()
; #define PG8_SCHED __builtin_amdgcn_sched_barrier(0)
; template <class Epi, class Sched, bool ALIGN_EPI = false, bool SP2 = false>
; __device__ __forceinline__ void gemm_phase(PG8_LAS unsigned char* lds, const Gemm g, const Sched& S, const Epi& E) {
;     ...
;             PG8_WAIT_V(8); PG8_WAIT_L(0); PG8_BAR; PG8_MMA(0, 0, At, B0); PG8_MMA(0, 1, At, B1); PG8_BAR; PG8_SCHED;
;             PG8_LDA(At, 0, 1); PG8_STAGE(PG8_SB(0, 0), b2, voffB); PG8_STAGE(PG8_SB(0, 1), b2 + hstep, voffB); PG8_STAGE(PG8_SA(0, 0), a2, voffA);
;             PG8_WAIT_V(8); PG8_WAIT_L(0); PG8_BAR; PG8_MMA(1, 0, At, B0); PG8_MMA(1, 1, At, B1); PG8_BAR; PG8_SCHED;
;             PG8_LDB(B0, 1, 0); PG8_LDB(B1, 1, 1); PG8_SCHED; PG8_LDA(At, 1, 0); PG8_STAGE(PG8_SA(0, 1), a2 + hstep, voffA);
	s_waitcnt lgkmcnt(0)
	v_mfma_f32_16x16x32_bf16 v[124:127], v[138:141], v[192:195], v[124:127]
	v_mfma_f32_16x16x32_bf16 v[120:123], v[168:171], v[192:195], v[120:123]
	v_mfma_f32_16x16x32_bf16 v[108:111], v[138:141], v[200:203], v[108:111]
	v_mfma_f32_16x16x32_bf16 v[104:107], v[168:171], v[200:203], v[104:107]
	v_mfma_f32_16x16x32_bf16 v[92:95], v[138:141], v[208:211], v[92:95]
	v_mfma_f32_16x16x32_bf16 v[88:91], v[168:171], v[208:211], v[88:91]
	v_mfma_f32_16x16x32_bf16 v[76:79], v[138:141], v[216:219], v[76:79]
	v_mfma_f32_16x16x32_bf16 v[72:75], v[168:171], v[216:219], v[72:75]
	v_mfma_f32_16x16x32_bf16 v[124:127], v[142:145], v[196:199], v[124:127]
	v_mfma_f32_16x16x32_bf16 v[120:123], v[172:175], v[196:199], v[120:123]
	v_mfma_f32_16x16x32_bf16 v[108:111], v[142:145], v[204:207], v[108:111]
	v_mfma_f32_16x16x32_bf16 v[104:107], v[172:175], v[204:207], v[104:107]
	v_mfma_f32_16x16x32_bf16 v[92:95], v[142:145], v[212:215], v[92:95]
	v_mfma_f32_16x16x32_bf16 v[88:91], v[172:175], v[212:215], v[88:91]
	v_mfma_f32_16x16x32_bf16 v[76:79], v[142:145], v[220:223], v[76:79]
	v_mfma_f32_16x16x32_bf16 v[72:75], v[172:175], v[220:223], v[72:75]
	v_mfma_f32_16x16x32_bf16 v[116:119], v[176:179], v[192:195], v[116:119]
	v_mfma_f32_16x16x32_bf16 v[112:115], v[184:187], v[192:195], v[112:115]
	v_mfma_f32_16x16x32_bf16 v[100:103], v[176:179], v[200:203], v[100:103]
	v_mfma_f32_16x16x32_bf16 v[96:99], v[184:187], v[200:203], v[96:99]
	v_mfma_f32_16x16x32_bf16 v[84:87], v[176:179], v[208:211], v[84:87]
	v_mfma_f32_16x16x32_bf16 v[80:83], v[184:187], v[208:211], v[80:83]
	v_mfma_f32_16x16x32_bf16 v[68:71], v[176:179], v[216:219], v[68:71]
	v_mfma_f32_16x16x32_bf16 v[64:67], v[184:187], v[216:219], v[64:67]
	v_mfma_f32_16x16x32_bf16 v[116:119], v[180:183], v[196:199], v[116:119]
	v_mfma_f32_16x16x32_bf16 v[112:115], v[188:191], v[196:199], v[112:115]
	v_mfma_f32_16x16x32_bf16 v[100:103], v[180:183], v[204:207], v[100:103]
	v_mfma_f32_16x16x32_bf16 v[96:99], v[188:191], v[204:207], v[96:99]
	v_mfma_f32_16x16x32_bf16 v[84:87], v[180:183], v[212:215], v[84:87]
	v_mfma_f32_16x16x32_bf16 v[80:83], v[188:191], v[212:215], v[80:83]
	v_mfma_f32_16x16x32_bf16 v[68:71], v[180:183], v[220:223], v[68:71]
	v_mfma_f32_16x16x32_bf16 v[64:67], v[188:191], v[220:223], v[64:67]
	s_barrier
	s_add_i32 s51, s51, s21
	v_lshl_add_u64 v[146:147], s[12:13], 0, v[156:157]
	s_mov_b32 m0, s51
	ds_read_b128 v[192:195], v152 offset:16384
	ds_read_b128 v[196:199], v152 offset:17408
	ds_read_b128 v[200:203], v152 offset:18432
	ds_read_b128 v[204:207], v152 offset:19456
	ds_read_b128 v[208:211], v152 offset:20480
	ds_read_b128 v[212:215], v152 offset:21504
	ds_read_b128 v[216:219], v152 offset:22528
	ds_read_b128 v[220:223], v152 offset:23552
	global_load_lds_dwordx4 v[146:147], off
	s_add_i32 m0, s51, 0x2000
	s_add_u32 s52, s12, 0x40000
	v_lshl_add_u64 v[154:155], s[12:13], 0, v[128:129]
	s_addc_u32 s53, s13, 0
	s_add_i32 s51, s54, s21
	global_load_lds_dwordx4 v[154:155], off
	v_lshl_add_u64 v[224:225], s[52:53], 0, v[156:157]
	s_mov_b32 m0, s51
	v_lshl_add_u64 v[226:227], s[14:15], 0, v[130:131]
	global_load_lds_dwordx4 v[224:225], off
	v_lshl_add_u64 v[224:225], s[52:53], 0, v[128:129]
	s_add_i32 m0, s51, 0x2000
	s_nop 0
	global_load_lds_dwordx4 v[224:225], off
	v_lshl_add_u64 v[224:225], s[14:15], 0, v[132:133]
	s_mov_b32 m0, s25
	s_nop 0
	global_load_lds_dwordx4 v[224:225], off
	s_mov_b32 m0, s26
	s_nop 0
	global_load_lds_dwordx4 v[226:227], off
	s_waitcnt vmcnt(8)
	s_waitcnt lgkmcnt(0)
	s_barrier
	s_waitcnt lgkmcnt(0)
	v_mfma_f32_16x16x32_bf16 v[60:63], v[138:141], v[192:195], v[60:63]
	v_mfma_f32_16x16x32_bf16 v[56:59], v[168:171], v[192:195], v[56:59]
	v_mfma_f32_16x16x32_bf16 v[44:47], v[138:141], v[200:203], v[44:47]
	v_mfma_f32_16x16x32_bf16 v[40:43], v[168:171], v[200:203], v[40:43]
	v_mfma_f32_16x16x32_bf16 v[28:31], v[138:141], v[208:211], v[28:31]
	v_mfma_f32_16x16x32_bf16 v[24:27], v[168:171], v[208:211], v[24:27]
	v_mfma_f32_16x16x32_bf16 v[12:15], v[138:141], v[216:219], v[12:15]
	v_mfma_f32_16x16x32_bf16 v[8:11], v[168:171], v[216:219], v[8:11]
	v_mfma_f32_16x16x32_bf16 v[60:63], v[142:145], v[196:199], v[60:63]
	v_mfma_f32_16x16x32_bf16 v[56:59], v[172:175], v[196:199], v[56:59]
	v_mfma_f32_16x16x32_bf16 v[44:47], v[142:145], v[204:207], v[44:47]
	v_mfma_f32_16x16x32_bf16 v[40:43], v[172:175], v[204:207], v[40:43]
	v_mfma_f32_16x16x32_bf16 v[28:31], v[142:145], v[212:215], v[28:31]
	v_mfma_f32_16x16x32_bf16 v[24:27], v[172:175], v[212:215], v[24:27]
	v_mfma_f32_16x16x32_bf16 v[12:15], v[142:145], v[220:223], v[12:15]
	v_mfma_f32_16x16x32_bf16 v[8:11], v[172:175], v[220:223], v[8:11]
	v_mfma_f32_16x16x32_bf16 v[52:55], v[176:179], v[192:195], v[52:55]
	v_mfma_f32_16x16x32_bf16 v[48:51], v[184:187], v[192:195], v[48:51]
	v_mfma_f32_16x16x32_bf16 v[36:39], v[176:179], v[200:203], v[36:39]
	v_mfma_f32_16x16x32_bf16 v[32:35], v[184:187], v[200:203], v[32:35]
	v_mfma_f32_16x16x32_bf16 v[20:23], v[176:179], v[208:211], v[20:23]
	v_mfma_f32_16x16x32_bf16 v[16:19], v[184:187], v[208:211], v[16:19]
	v_mfma_f32_16x16x32_bf16 v[4:7], v[176:179], v[216:219], v[4:7]
	v_mfma_f32_16x16x32_bf16 v[0:3], v[184:187], v[216:219], v[0:3]
	v_mfma_f32_16x16x32_bf16 v[52:55], v[180:183], v[196:199], v[52:55]
	v_mfma_f32_16x16x32_bf16 v[48:51], v[188:191], v[196:199], v[48:51]
	v_mfma_f32_16x16x32_bf16 v[36:39], v[180:183], v[204:207], v[36:39]
	v_mfma_f32_16x16x32_bf16 v[32:35], v[188:191], v[204:207], v[32:35]
	v_mfma_f32_16x16x32_bf16 v[20:23], v[180:183], v[212:215], v[20:23]
	v_mfma_f32_16x16x32_bf16 v[16:19], v[188:191], v[212:215], v[16:19]
	v_mfma_f32_16x16x32_bf16 v[4:7], v[180:183], v[220:223], v[4:7]
	v_mfma_f32_16x16x32_bf16 v[0:3], v[188:191], v[220:223], v[0:3]
	s_barrier
; #define PG8_STAGE(bufoff, gbase, voff) do { _Pragma("unroll") for (int _i = 0; _i < 2; ++_i) \
;         __builtin_amdgcn_global_load_lds((const unsigned*)((const char*)(gbase) + (voff)[_i]), (PG8_LAS unsigned*)(lds + (bufoff) + ldsw + _i * 8192), 16, 0, 0); } while (0)
; #define PG8_LDA(dst, b, h) do { _Pragma("unroll") for (int m = 0; m < 4; ++m) _Pragma("unroll") for (int k = 0; k < 2; ++k) dst[m][k] = *(const PG8_LAS bf16x8*)(lds + PG8_SA(b, h) + aoff + m * 2048 + k * 1024); } while (0)
; #define PG8_LDB(dst, b, h) do { _Pragma("unroll") for (int n = 0; n < 2; ++n) _Pragma("unroll") for (int k = 0; k < 2; ++k) dst[n][k] = *(const PG8_LAS bf16x8*)(lds + PG8_SB(b, h) + boff + n * 2048 + k * 1024); } while (0)
; #define PG8_MMA(ai, bj, At, Bt) do { __builtin_amdgcn_s_setprio(1); _Pragma("unroll") for (int m = 0; m < 4; ++m) _Pragma("unroll") for (int n = 0; n < 2; ++n) _Pragma("unroll") for (int k = 0; k < 2; ++k) \
;         acc[ai][bj][m][n] = __builtin_amdgcn_mfma_f32_16x16x32_bf16(Bt[n][k], At[m][k], acc[ai][bj][m][n], 0, 0, 0); __builtin_amdgcn_s_setprio(0); } while (0)
; #define PG8_WAIT_V(n) asm volatile("s_waitcnt vmcnt(" #n ")" ::: "memory")
; #define PG8_WAIT_L(n) asm volatile("s_waitcnt lgkmcnt(" #n ")" ::: "memory")
; #define PG8_BAR __builtin_amdgcn_s_barrier()
; #define PG8_SCHED __builtin_amdgcn_sched_barrier(0)
; template <class Epi, class Sched, bool ALIGN_EPI = false, bool SP2 = false>
; __device__ __forceinline__ void gemm_phase(PG8_LAS unsigned char* lds, const Gemm g, const Sched& S, const Epi& E) {
;     ...
;             PG8_LDB(B0, 1, 0); PG8_LDB(B1, 1, 1); PG8_SCHED; PG8_LDA(At, 1, 0); PG8_STAGE(PG8_SA(0, 1), a2 + hstep, voffA);
;             PG8_WAIT_V(8); PG8_WAIT_L(0); PG8_BAR; PG8_MMA(0, 0, At, B0); PG8_MMA(0, 1, At, B1); PG8_BAR; PG8_SCHED;
	s_add_i32 s51, 0, 0x18000
	v_add_u32_e32 v153, s51, v149
	s_add_i32 s52, 0, 0x1c000
	ds_read_b128 v[138:141], v153
	ds_read_b128 v[142:145], v153 offset:1024
	ds_read_b128 v[168:171], v153 offset:2048
	ds_read_b128 v[172:175], v153 offset:3072
	v_add_u32_e32 v153, s52, v149
	ds_read_b128 v[176:179], v153
	ds_read_b128 v[180:183], v153 offset:1024
	ds_read_b128 v[184:187], v153 offset:2048
	ds_read_b128 v[188:191], v153 offset:3072
	s_add_u32 s14, s14, 0x40000
	s_addc_u32 s15, s15, 0
	s_mov_b32 m0, s27
	v_lshl_add_u64 v[228:229], s[14:15], 0, v[132:133]
	ds_read_b128 v[192:195], v152 offset:32768
	ds_read_b128 v[196:199], v152 offset:33792
	ds_read_b128 v[200:203], v152 offset:34816
	ds_read_b128 v[204:207], v152 offset:35840
	ds_read_b128 v[208:211], v152 offset:36864
	ds_read_b128 v[212:215], v152 offset:37888
	ds_read_b128 v[216:219], v152 offset:38912
	ds_read_b128 v[220:223], v152 offset:39936
	global_load_lds_dwordx4 v[228:229], off
	v_lshl_add_u64 v[228:229], s[14:15], 0, v[130:131]
	s_mov_b32 m0, s28
	s_nop 0
	global_load_lds_dwordx4 v[228:229], off
	s_waitcnt vmcnt(8)
	s_waitcnt lgkmcnt(0)
	s_barrier
	s_waitcnt lgkmcnt(0)
	v_mfma_f32_16x16x32_bf16 v[124:127], v[138:141], v[192:195], v[124:127]
	v_mfma_f32_16x16x32_bf16 v[120:123], v[168:171], v[192:195], v[120:123]
	v_mfma_f32_16x16x32_bf16 v[108:111], v[138:141], v[200:203], v[108:111]
	v_mfma_f32_16x16x32_bf16 v[104:107], v[168:171], v[200:203], v[104:107]
	v_mfma_f32_16x16x32_bf16 v[92:95], v[138:141], v[208:211], v[92:95]
	v_mfma_f32_16x16x32_bf16 v[88:91], v[168:171], v[208:211], v[88:91]
	v_mfma_f32_16x16x32_bf16 v[76:79], v[138:141], v[216:219], v[76:79]
	v_mfma_f32_16x16x32_bf16 v[72:75], v[168:171], v[216:219], v[72:75]
	v_mfma_f32_16x16x32_bf16 v[124:127], v[142:145], v[196:199], v[124:127]
	v_mfma_f32_16x16x32_bf16 v[120:123], v[172:175], v[196:199], v[120:123]
	v_mfma_f32_16x16x32_bf16 v[108:111], v[142:145], v[204:207], v[108:111]
	v_mfma_f32_16x16x32_bf16 v[104:107], v[172:175], v[204:207], v[104:107]
	v_mfma_f32_16x16x32_bf16 v[92:95], v[142:145], v[212:215], v[92:95]
	v_mfma_f32_16x16x32_bf16 v[88:91], v[172:175], v[212:215], v[88:91]
	v_mfma_f32_16x16x32_bf16 v[76:79], v[142:145], v[220:223], v[76:79]
	v_mfma_f32_16x16x32_bf16 v[72:75], v[172:175], v[220:223], v[72:75]
	v_mfma_f32_16x16x32_bf16 v[116:119], v[176:179], v[192:195], v[116:119]
	v_mfma_f32_16x16x32_bf16 v[112:115], v[184:187], v[192:195], v[112:115]
	v_mfma_f32_16x16x32_bf16 v[100:103], v[176:179], v[200:203], v[100:103]
	v_mfma_f32_16x16x32_bf16 v[96:99], v[184:187], v[200:203], v[96:99]
	v_mfma_f32_16x16x32_bf16 v[84:87], v[176:179], v[208:211], v[84:87]
	v_mfma_f32_16x16x32_bf16 v[80:83], v[184:187], v[208:211], v[80:83]
	v_mfma_f32_16x16x32_bf16 v[68:71], v[176:179], v[216:219], v[68:71]
	v_mfma_f32_16x16x32_bf16 v[64:67], v[184:187], v[216:219], v[64:67]
	v_mfma_f32_16x16x32_bf16 v[116:119], v[180:183], v[196:199], v[116:119]
	v_mfma_f32_16x16x32_bf16 v[112:115], v[188:191], v[196:199], v[112:115]
	v_mfma_f32_16x16x32_bf16 v[100:103], v[180:183], v[204:207], v[100:103]
	v_mfma_f32_16x16x32_bf16 v[96:99], v[188:191], v[204:207], v[96:99]
	v_mfma_f32_16x16x32_bf16 v[84:87], v[180:183], v[212:215], v[84:87]
	v_mfma_f32_16x16x32_bf16 v[80:83], v[188:191], v[212:215], v[80:83]
	v_mfma_f32_16x16x32_bf16 v[68:71], v[180:183], v[220:223], v[68:71]
	v_mfma_f32_16x16x32_bf16 v[64:67], v[188:191], v[220:223], v[64:67]
	s_barrier
; #define PG8_STAGE(bufoff, gbase, voff) do { _Pragma("unroll") for (int _i = 0; _i < 2; ++_i) \
;         __builtin_amdgcn_global_load_lds((const unsigned*)((const char*)(gbase) + (voff)[_i]), (PG8_LAS unsigned*)(lds + (bufoff) + ldsw + _i * 8192), 16, 0, 0); } while (0)
; #define PG8_LDA(dst, b, h) do { _Pragma("unroll") for (int m = 0; m < 4; ++m) _Pragma("unroll") for (int k = 0; k < 2; ++k) dst[m][k] = *(const PG8_LAS bf16x8*)(lds + PG8_SA(b, h) + aoff + m * 2048 + k * 1024); } while (0)
; #define PG8_MMA(ai, bj, At, Bt) do { __builtin_amdgcn_s_setprio(1); _Pragma("unroll") for (int m = 0; m < 4; ++m) _Pragma("unroll") for (int n = 0; n < 2; ++n) _Pragma("unroll") for (int k = 0; k < 2; ++k) \
;         acc[ai][bj][m][n] = __builtin_amdgcn_mfma_f32_16x16x32_bf16(Bt[n][k], At[m][k], acc[ai][bj][m][n], 0, 0, 0); __builtin_amdgcn_s_setprio(0); } while (0)
; #define PG8_WAIT_V(n) asm volatile("s_waitcnt vmcnt(" #n ")" ::: "memory")
; #define PG8_WAIT_L(n) asm volatile("s_waitcnt lgkmcnt(" #n ")" ::: "memory")
; #define PG8_BAR __builtin_amdgcn_s_barrier()
; #define PG8_SCHED __builtin_amdgcn_sched_barrier(0)
; template <class Epi, class Sched, bool ALIGN_EPI = false, bool SP2 = false>
; __device__ __forceinline__ void gemm_phase(PG8_LAS unsigned char* lds, const Gemm g, const Sched& S, const Epi& E) {
;     ...
;         for (int t = 0; t < nt; t += 2) {
;             const bool last = (t == nt - 2);
;             const char* a1 = cA + (size_t)(t + 1) * kstep;
;             const char* a2 = last ? nA : cA + (size_t)(t + 2) * kstep; const char* b2 = last ? nB : cB + (size_t)(t + 2) * kstep;
;             const char* a3 = a2 + kstep; const char* b3 = b2 + kstep;
;     ...
;             PG8_LDA(At, 1, 1); PG8_STAGE(PG8_SB(1, 0), b3, voffB); PG8_STAGE(PG8_SB(1, 1), b3 + hstep, voffB); PG8_STAGE(PG8_SA(1, 0), a3, voffA);
;             PG8_WAIT_V(8); PG8_WAIT_L(0); PG8_BAR; PG8_MMA(1, 0, At, B0); PG8_MMA(1, 1, At, B1); PG8_BAR; PG8_SCHED;
	s_add_i32 s14, s51, s21
	v_lshl_add_u64 v[146:147], v[146:147], 0, s[96:97]
	s_mov_b32 m0, s14
	ds_read_b128 v[192:195], v152 offset:49152
	ds_read_b128 v[196:199], v152 offset:50176
	ds_read_b128 v[200:203], v152 offset:51200
	ds_read_b128 v[204:207], v152 offset:52224
	ds_read_b128 v[208:211], v152 offset:53248
	ds_read_b128 v[212:215], v152 offset:54272
	ds_read_b128 v[216:219], v152 offset:55296
	ds_read_b128 v[220:223], v152 offset:56320
	global_load_lds_dwordx4 v[146:147], off
	s_add_i32 m0, s14, 0x2000
	s_add_u32 s12, s12, 0x40080
	v_lshl_add_u64 v[146:147], v[154:155], 0, s[96:97]
	s_addc_u32 s13, s13, 0
	s_add_i32 s14, s52, s21
	global_load_lds_dwordx4 v[146:147], off
	v_lshl_add_u64 v[146:147], s[12:13], 0, v[156:157]
	s_mov_b32 m0, s14
	s_nop 0
	global_load_lds_dwordx4 v[146:147], off
	v_lshl_add_u64 v[146:147], s[12:13], 0, v[128:129]
	s_add_i32 m0, s14, 0x2000
	s_nop 0
	global_load_lds_dwordx4 v[146:147], off
	v_lshl_add_u64 v[146:147], v[224:225], 0, s[96:97]
	s_mov_b32 m0, s29
	s_nop 0
	global_load_lds_dwordx4 v[146:147], off
	v_lshl_add_u64 v[146:147], v[226:227], 0, s[96:97]
	s_mov_b32 m0, s30
	s_nop 0
	global_load_lds_dwordx4 v[146:147], off
	s_waitcnt vmcnt(8)
	s_waitcnt lgkmcnt(0)
	s_barrier
	s_waitcnt lgkmcnt(0)
	v_mfma_f32_16x16x32_bf16 v[60:63], v[138:141], v[192:195], v[60:63]
	v_mfma_f32_16x16x32_bf16 v[56:59], v[168:171], v[192:195], v[56:59]
	v_mfma_f32_16x16x32_bf16 v[44:47], v[138:141], v[200:203], v[44:47]
	v_mfma_f32_16x16x32_bf16 v[40:43], v[168:171], v[200:203], v[40:43]
	s_add_i32 s50, s50, 2
	s_add_u32 s10, s10, 0x100
	s_addc_u32 s11, s11, 0
	s_add_u32 s48, s48, 0x100
	s_addc_u32 s49, s49, 0
	s_add_u32 s12, s10, 0xfffc0080
	s_addc_u32 s13, s11, -1
	s_add_i32 s51, 0, 0x10000
	s_cmp_eq_u32 s50, 12
	s_cselect_b32 s15, s41, s13
	s_cselect_b32 s14, s46, s12
	s_cselect_b32 s13, s9, s49
	s_cselect_b32 s12, s47, s48
	s_add_i32 s54, 0, 0x14000
	v_mfma_f32_16x16x32_bf16 v[28:31], v[138:141], v[208:211], v[28:31]
	v_mfma_f32_16x16x32_bf16 v[24:27], v[168:171], v[208:211], v[24:27]
	v_mfma_f32_16x16x32_bf16 v[12:15], v[138:141], v[216:219], v[12:15]
	v_mfma_f32_16x16x32_bf16 v[8:11], v[168:171], v[216:219], v[8:11]
	v_mfma_f32_16x16x32_bf16 v[60:63], v[142:145], v[196:199], v[60:63]
	v_mfma_f32_16x16x32_bf16 v[56:59], v[172:175], v[196:199], v[56:59]
	v_mfma_f32_16x16x32_bf16 v[44:47], v[142:145], v[204:207], v[44:47]
	v_mfma_f32_16x16x32_bf16 v[40:43], v[172:175], v[204:207], v[40:43]
	v_mfma_f32_16x16x32_bf16 v[28:31], v[142:145], v[212:215], v[28:31]
	v_mfma_f32_16x16x32_bf16 v[24:27], v[172:175], v[212:215], v[24:27]
	v_mfma_f32_16x16x32_bf16 v[12:15], v[142:145], v[220:223], v[12:15]
	v_mfma_f32_16x16x32_bf16 v[8:11], v[172:175], v[220:223], v[8:11]
	v_mfma_f32_16x16x32_bf16 v[52:55], v[176:179], v[192:195], v[52:55]
	v_mfma_f32_16x16x32_bf16 v[48:51], v[184:187], v[192:195], v[48:51]
	v_mfma_f32_16x16x32_bf16 v[36:39], v[176:179], v[200:203], v[36:39]
	v_mfma_f32_16x16x32_bf16 v[32:35], v[184:187], v[200:203], v[32:35]
	v_mfma_f32_16x16x32_bf16 v[20:23], v[176:179], v[208:211], v[20:23]
	v_mfma_f32_16x16x32_bf16 v[16:19], v[184:187], v[208:211], v[16:19]
	v_mfma_f32_16x16x32_bf16 v[4:7], v[176:179], v[216:219], v[4:7]
	v_mfma_f32_16x16x32_bf16 v[0:3], v[184:187], v[216:219], v[0:3]
	v_mfma_f32_16x16x32_bf16 v[52:55], v[180:183], v[196:199], v[52:55]
	v_mfma_f32_16x16x32_bf16 v[48:51], v[188:191], v[196:199], v[48:51]
	v_mfma_f32_16x16x32_bf16 v[36:39], v[180:183], v[204:207], v[36:39]
	v_mfma_f32_16x16x32_bf16 v[32:35], v[188:191], v[204:207], v[32:35]
	v_mfma_f32_16x16x32_bf16 v[20:23], v[180:183], v[212:215], v[20:23]
	v_mfma_f32_16x16x32_bf16 v[16:19], v[188:191], v[212:215], v[16:19]
	v_mfma_f32_16x16x32_bf16 v[4:7], v[180:183], v[220:223], v[4:7]
	v_mfma_f32_16x16x32_bf16 v[0:3], v[188:191], v[220:223], v[0:3]
	s_barrier
	s_cmp_gt_u32 s50, 13
	s_cbranch_scc0 .LBB0_399
	s_and_b64 vcc, exec, s[6:7]
	s_cbranch_vccz .LBB0_402
	s_barrier
